# MLA: next unit's first loads (Q, K pairs 0-1, V0-V2) issued before the last slot of the current unit, landing in the idle S buffer
# baseline (speedup 1.0000x reference)
.LBB0_1885:
	s_or_b64 exec, exec, s[0:1]
	v_readlane_b32 s0, v250, 2
	v_readlane_b32 s1, v250, 3
	v_readlane_b32 s86, v250, 1
	s_andn2_b64 vcc, exec, s[0:1]
	s_waitcnt vmcnt(0) lgkmcnt(0)
	s_barrier
	s_cbranch_vccnz .LBB0_1920
	v_and_b32_e32 v234, 31, v0
	v_bfe_u32 v235, v0, 5, 1
	v_mul_u32_u24_e32 v220, 0xd0, v234
	v_lshl_add_u32 v220, v235, 4, v220
	v_mul_u32_u24_e32 v221, 0x88, v234
	v_lshl_add_u32 v221, v235, 3, v221
	v_add_u32_e32 v221, 0xd000, v221
	v_lshl_or_b32 v1, s87, 5, v234
	v_mul_u32_u24_e32 v237, 0xc0, v1
	v_lshl_add_u32 v237, v235, 4, v237
	v_lshlrev_b32_e32 v236, 10, v1
	v_lshl_add_u32 v236, v235, 3, v236
	v_lshlrev_b32_e32 v226, 4, v0
	v_add_u32_e32 v227, 0x2000, v226
	v_add_u32_e32 v228, 0x4000, v226
	v_lshrrev_b32_e32 v234, 3, v0
	v_and_b32_e32 v235, 7, v0
	v_mul_u32_u24_e32 v229, 0x2200, v234
	v_lshl_add_u32 v229, v235, 4, v229
	v_mul_u32_u24_e32 v225, 0x88, v234
	v_lshl_add_u32 v225, v235, 4, v225
	v_add_u32_e32 v225, 0xd000, v225
	s_mov_b32 s17, 0xaaab
	s_movk_i32 s18, 0xd0
	v_mov_b32_e32 v234, v0
	v_mul_lo_u32 v235, v234, s17
	v_lshrrev_b32_e32 v235, 19, v235
	v_mul_u32_u24_e32 v1, 12, v235
	v_sub_u32_e32 v234, v234, v1
	v_lshrrev_b32_e32 v1, 6, v235
	v_and_b32_e32 v235, 63, v235
	v_mul_u32_u24_e32 v1, 0x3400, v1
	v_mad_u32_u24 v1, v235, s18, v1
	v_lshl_add_u32 v222, v234, 4, v1
	v_add_u32_e32 v234, 512, v0
	v_mul_lo_u32 v235, v234, s17
	v_lshrrev_b32_e32 v235, 19, v235
	v_mul_u32_u24_e32 v1, 12, v235
	v_sub_u32_e32 v234, v234, v1
	v_lshrrev_b32_e32 v1, 6, v235
	v_and_b32_e32 v235, 63, v235
	v_mul_u32_u24_e32 v1, 0x3400, v1
	v_mad_u32_u24 v1, v235, s18, v1
	v_lshl_add_u32 v223, v234, 4, v1
	v_add_u32_e32 v234, 1024, v0
	v_mul_lo_u32 v235, v234, s17
	v_lshrrev_b32_e32 v235, 19, v235
	v_mul_u32_u24_e32 v1, 12, v235
	v_sub_u32_e32 v234, v234, v1
	v_lshrrev_b32_e32 v1, 6, v235
	v_and_b32_e32 v235, 63, v235
	v_mul_u32_u24_e32 v1, 0x3400, v1
	v_mad_u32_u24 v1, v235, s18, v1
	v_lshl_add_u32 v224, v234, 4, v1
	s_lshr_b32 s17, s2, 4
	s_and_b32 s18, s2, 15
	s_mul_i32 s19, s17, 0xcc000
	s_add_u32 s4, s78, s19
	s_addc_u32 s5, s79, 0
	s_mul_i32 s19, s17, 0x88000
	s_add_u32 s19, s19, 0x1a00000
	s_add_u32 s10, s78, s19
	s_addc_u32 s11, s79, 0
	s_lshl_b32 s19, s17, 12
	s_lshl_b32 s20, s18, 8
	s_add_u32 s19, s19, s20
	s_mul_i32 s19, s19, 0xc0
	s_add_u32 s19, s19, 0x1400000
	s_add_u32 s12, s80, s19
	s_addc_u32 s13, s81, 0
	s_lshr_b32 s19, s17, 3
	s_lshl_b32 s19, s19, 12
	s_add_u32 s19, s19, s20
	s_lshl_b32 s19, s19, 10
	s_and_b32 s21, s17, 7
	s_lshl_b32 s21, s21, 7
	s_add_u32 s19, s19, s21
	s_add_u32 s19, s19, 0x7900000
	s_add_u32 s14, s80, s19
	s_addc_u32 s15, s81, 0
	global_load_dwordx4 v[98:101], v237, s[12:13] offset:0
	global_load_dwordx4 v[102:105], v237, s[12:13] offset:32
	global_load_dwordx4 v[106:109], v237, s[12:13] offset:64
	global_load_dwordx4 v[110:113], v237, s[12:13] offset:96
	global_load_dwordx4 v[114:117], v237, s[12:13] offset:128
	global_load_dwordx4 v[118:121], v237, s[12:13] offset:160
	global_load_dwordx4 v[34:37], v226, s[4:5]
	global_load_dwordx4 v[38:41], v227, s[4:5]
	global_load_dwordx4 v[42:45], v228, s[4:5]
	global_load_dwordx4 v[46:49], v229, s[10:11]
	s_add_u32 s4, s4, 0x6000
	s_addc_u32 s5, s5, 0
	global_load_dwordx4 v[50:53], v226, s[4:5]
	global_load_dwordx4 v[54:57], v227, s[4:5]
	global_load_dwordx4 v[58:61], v228, s[4:5]
	global_load_dwordx4 v[62:65], v229, s[10:11] offset:128
	global_load_dwordx4 v[216:219], v229, s[10:11] offset:256
	s_add_u32 s4, s4, 0x6000
	s_addc_u32 s5, s5, 0
	s_add_u32 s10, s10, 0x180
	s_addc_u32 s11, s11, 0
	v_mov_b32_e32 v2, 0
	v_mov_b32_e32 v3, 0
	v_mov_b32_e32 v4, 0
	v_mov_b32_e32 v5, 0
	v_mov_b32_e32 v6, 0
	v_mov_b32_e32 v7, 0
	v_mov_b32_e32 v8, 0
	v_mov_b32_e32 v9, 0
	v_mov_b32_e32 v10, 0
	v_mov_b32_e32 v11, 0
	v_mov_b32_e32 v12, 0
	v_mov_b32_e32 v13, 0
	v_mov_b32_e32 v14, 0
	v_mov_b32_e32 v15, 0
	v_mov_b32_e32 v16, 0
	v_mov_b32_e32 v17, 0
	v_mov_b32_e32 v18, 0
	v_mov_b32_e32 v19, 0
	v_mov_b32_e32 v20, 0
	v_mov_b32_e32 v21, 0
	v_mov_b32_e32 v22, 0
	v_mov_b32_e32 v23, 0
	v_mov_b32_e32 v24, 0
	v_mov_b32_e32 v25, 0
	v_mov_b32_e32 v26, 0
	v_mov_b32_e32 v27, 0
	v_mov_b32_e32 v28, 0
	v_mov_b32_e32 v29, 0
	v_mov_b32_e32 v30, 0
	v_mov_b32_e32 v31, 0
	v_mov_b32_e32 v32, 0
	v_mov_b32_e32 v33, 0
	v_mov_b32_e32 v122, 0
	v_mov_b32_e32 v123, 0
	v_mov_b32_e32 v124, 0
	v_mov_b32_e32 v125, 0
	v_mov_b32_e32 v126, 0
	v_mov_b32_e32 v127, 0
	v_mov_b32_e32 v128, 0
	v_mov_b32_e32 v129, 0
	v_mov_b32_e32 v130, 0
	v_mov_b32_e32 v131, 0
	v_mov_b32_e32 v132, 0
	v_mov_b32_e32 v133, 0
	v_mov_b32_e32 v134, 0
	v_mov_b32_e32 v135, 0
	v_mov_b32_e32 v136, 0
	v_mov_b32_e32 v137, 0
	v_mov_b32_e32 v230, 0
	v_mov_b32_e32 v231, 0
	v_mov_b32_e32 v232, 0
	s_waitcnt vmcnt(5)
	ds_write_b128 v222, v[34:37]
	ds_write_b128 v223, v[38:41]
	ds_write_b128 v224, v[42:45]
	ds_write_b64 v225, v[46:47]
	ds_write_b64 v225, v[48:49] offset:8
	s_waitcnt vmcnt(1)
	ds_write_b128 v222, v[50:53] offset:26624
	ds_write_b128 v223, v[54:57] offset:26624
	ds_write_b128 v224, v[58:61] offset:26624
	ds_write_b64 v225, v[62:63] offset:8704
	ds_write_b64 v225, v[64:65] offset:8712
	s_waitcnt lgkmcnt(0)
	s_barrier
.Lmla_body:
	ds_read_b128 v[138:141], v220 offset:0
	ds_read_b128 v[142:145], v220 offset:6656
	ds_read_b128 v[146:149], v220 offset:32
	ds_read_b128 v[150:153], v220 offset:6688
	ds_read_b128 v[154:157], v220 offset:64
	ds_read_b128 v[158:161], v220 offset:6720
	ds_read_b128 v[66:69], v220 offset:96
	ds_read_b128 v[70:73], v220 offset:6752
	ds_read_b128 v[74:77], v220 offset:128
	ds_read_b128 v[78:81], v220 offset:6784
	ds_read_b128 v[82:85], v220 offset:160
	ds_read_b128 v[86:89], v220 offset:6816
	s_waitcnt lgkmcnt(11)
	v_mfma_f32_32x32x16_bf16 v[34:49], v[138:141], v[98:101], v[122:137]
	s_waitcnt lgkmcnt(10)
	v_mfma_f32_32x32x16_bf16 v[50:65], v[142:145], v[98:101], v[122:137]
	s_waitcnt lgkmcnt(9)
	v_mfma_f32_32x32x16_bf16 v[34:49], v[146:149], v[102:105], v[34:49]
	s_waitcnt lgkmcnt(8)
	v_mfma_f32_32x32x16_bf16 v[50:65], v[150:153], v[102:105], v[50:65]
	s_waitcnt lgkmcnt(7)
	v_mfma_f32_32x32x16_bf16 v[34:49], v[154:157], v[106:109], v[34:49]
	s_waitcnt lgkmcnt(6)
	v_mfma_f32_32x32x16_bf16 v[50:65], v[158:161], v[106:109], v[50:65]
	s_waitcnt lgkmcnt(5)
	v_mfma_f32_32x32x16_bf16 v[34:49], v[66:69], v[110:113], v[34:49]
	s_waitcnt lgkmcnt(4)
	v_mfma_f32_32x32x16_bf16 v[50:65], v[70:73], v[110:113], v[50:65]
	s_waitcnt lgkmcnt(3)
	v_mfma_f32_32x32x16_bf16 v[34:49], v[74:77], v[114:117], v[34:49]
	s_waitcnt lgkmcnt(2)
	v_mfma_f32_32x32x16_bf16 v[50:65], v[78:81], v[114:117], v[50:65]
	s_waitcnt lgkmcnt(1)
	v_mfma_f32_32x32x16_bf16 v[34:49], v[82:85], v[118:121], v[34:49]
	s_waitcnt lgkmcnt(0)
	v_mfma_f32_32x32x16_bf16 v[50:65], v[86:89], v[118:121], v[50:65]
	s_nop 15
	v_max3_f32 v234, v34, v35, v36
	v_max3_f32 v235, v50, v51, v52
	v_max3_f32 v234, v234, v37, v38
	v_max3_f32 v235, v235, v53, v54
	v_max3_f32 v234, v234, v39, v40
	v_max3_f32 v235, v235, v55, v56
	v_max3_f32 v234, v234, v41, v42
	v_max3_f32 v235, v235, v57, v58
	v_max3_f32 v234, v234, v43, v44
	v_max3_f32 v235, v235, v59, v60
	v_max3_f32 v234, v234, v45, v46
	v_max3_f32 v235, v235, v61, v62
	v_max3_f32 v234, v234, v47, v48
	v_max3_f32 v235, v235, v63, v64
	v_max3_f32 v234, v234, v49, v65
	v_max_f32_e32 v234, v234, v235
	v_mov_b32_e32 v235, v234
	s_nop 1
	v_permlane32_swap_b32_e32 v234, v235
	v_max_f32_e32 v233, v234, v235
	s_nop 15
	v_add_f32_e32 v230, v230, v233
	v_sub_f32_e32 v34, v34, v233
	v_sub_f32_e32 v35, v35, v233
	v_sub_f32_e32 v36, v36, v233
	v_sub_f32_e32 v37, v37, v233
	v_sub_f32_e32 v38, v38, v233
	v_sub_f32_e32 v39, v39, v233
	v_sub_f32_e32 v40, v40, v233
	v_sub_f32_e32 v41, v41, v233
	v_sub_f32_e32 v42, v42, v233
	v_sub_f32_e32 v43, v43, v233
	v_sub_f32_e32 v44, v44, v233
	v_sub_f32_e32 v45, v45, v233
	v_sub_f32_e32 v46, v46, v233
	v_sub_f32_e32 v47, v47, v233
	v_sub_f32_e32 v48, v48, v233
	v_sub_f32_e32 v49, v49, v233
	v_sub_f32_e32 v50, v50, v233
	v_sub_f32_e32 v51, v51, v233
	v_sub_f32_e32 v52, v52, v233
	v_sub_f32_e32 v53, v53, v233
	v_sub_f32_e32 v54, v54, v233
	v_sub_f32_e32 v55, v55, v233
	v_sub_f32_e32 v56, v56, v233
	v_sub_f32_e32 v57, v57, v233
	v_sub_f32_e32 v58, v58, v233
	v_sub_f32_e32 v59, v59, v233
	v_sub_f32_e32 v60, v60, v233
	v_sub_f32_e32 v61, v61, v233
	v_sub_f32_e32 v62, v62, v233
	v_sub_f32_e32 v63, v63, v233
	v_sub_f32_e32 v64, v64, v233
	v_sub_f32_e32 v65, v65, v233
	v_sub_f32_e32 v122, 0, v230
	v_mov_b32_e32 v123, v122
	v_mov_b32_e32 v124, v122
	v_mov_b32_e32 v125, v122
	v_mov_b32_e32 v126, v122
	v_mov_b32_e32 v127, v122
	v_mov_b32_e32 v128, v122
	v_mov_b32_e32 v129, v122
	v_mov_b32_e32 v130, v122
	v_mov_b32_e32 v131, v122
	v_mov_b32_e32 v132, v122
	v_mov_b32_e32 v133, v122
	v_mov_b32_e32 v134, v122
	v_mov_b32_e32 v135, v122
	v_mov_b32_e32 v136, v122
	v_mov_b32_e32 v137, v122
	ds_read_b128 v[138:141], v220 offset:13312
	ds_read_b128 v[142:145], v220 offset:19968
	ds_read_b128 v[146:149], v220 offset:13344
	ds_read_b128 v[150:153], v220 offset:20000
	ds_read_b128 v[154:157], v220 offset:13376
	ds_read_b128 v[158:161], v220 offset:20032
	s_movk_i32 s16, 16

.Lmla_nr_t2:
	s_waitcnt lgkmcnt(0)
	s_barrier
	s_mov_b64 s[24:25], s[14:15]
	s_add_i32 s2, s2, s88
	s_cmpk_lt_i32 s2, 0x200
	s_cbranch_scc0 .Lmla_nopf
	s_lshr_b32 s17, s2, 4
	s_and_b32 s18, s2, 15
	s_mul_i32 s19, s17, 0xcc000
	s_add_u32 s4, s78, s19
	s_addc_u32 s5, s79, 0
	s_mul_i32 s19, s17, 0x88000
	s_add_u32 s19, s19, 0x1a00000
	s_add_u32 s10, s78, s19
	s_addc_u32 s11, s79, 0
	s_lshl_b32 s19, s17, 12
	s_lshl_b32 s20, s18, 8
	s_add_u32 s19, s19, s20
	s_mul_i32 s19, s19, 0xc0
	s_add_u32 s19, s19, 0x1400000
	s_add_u32 s12, s80, s19
	s_addc_u32 s13, s81, 0
	s_lshr_b32 s19, s17, 3
	s_lshl_b32 s19, s19, 12
	s_add_u32 s19, s19, s20
	s_lshl_b32 s19, s19, 10
	s_and_b32 s21, s17, 7
	s_lshl_b32 s21, s21, 7
	s_add_u32 s19, s19, s21
	s_add_u32 s19, s19, 0x7900000
	s_add_u32 s14, s80, s19
	s_addc_u32 s15, s81, 0
	global_load_dwordx4 v[98:101], v237, s[12:13] offset:0
	global_load_dwordx4 v[102:105], v237, s[12:13] offset:32
	global_load_dwordx4 v[106:109], v237, s[12:13] offset:64
	global_load_dwordx4 v[110:113], v237, s[12:13] offset:96
	global_load_dwordx4 v[114:117], v237, s[12:13] offset:128
	global_load_dwordx4 v[118:121], v237, s[12:13] offset:160
	global_load_dwordx4 v[34:37], v226, s[4:5]
	global_load_dwordx4 v[38:41], v227, s[4:5]
	global_load_dwordx4 v[42:45], v228, s[4:5]
	global_load_dwordx4 v[46:49], v229, s[10:11]
	s_add_u32 s4, s4, 0x6000
	s_addc_u32 s5, s5, 0
	global_load_dwordx4 v[50:53], v226, s[4:5]
	global_load_dwordx4 v[54:57], v227, s[4:5]
	global_load_dwordx4 v[58:61], v228, s[4:5]
	global_load_dwordx4 v[62:65], v229, s[10:11] offset:128
	global_load_dwordx4 v[216:219], v229, s[10:11] offset:256
	s_add_u32 s4, s4, 0x6000
	s_addc_u32 s5, s5, 0
	s_add_u32 s10, s10, 0x180
	s_addc_u32 s11, s11, 0
.Lmla_nopf:
	ds_read_b64 v[162:163], v221 offset:26112
	ds_read_b64 v[164:165], v221 offset:26128
	ds_read_b64 v[166:167], v221 offset:30464
	ds_read_b64 v[168:169], v221 offset:30480
	ds_read_b64 v[170:171], v221 offset:26144
	ds_read_b64 v[172:173], v221 offset:26160
	v_exp_f32_e32 v66, v66
	v_exp_f32_e32 v67, v67
	v_exp_f32_e32 v68, v68
	v_exp_f32_e32 v69, v69
	v_add_f32_e32 v231, v231, v66
	v_add_f32_e32 v232, v232, v67
	v_exp_f32_e32 v70, v70
	v_exp_f32_e32 v71, v71
	v_add_f32_e32 v231, v231, v68
	v_add_f32_e32 v232, v232, v69
	v_exp_f32_e32 v72, v72
	v_exp_f32_e32 v73, v73
	v_add_f32_e32 v231, v231, v70
	v_add_f32_e32 v232, v232, v71
	v_add_f32_e32 v231, v231, v72
	v_add_f32_e32 v232, v232, v73
	v_cvt_pk_bf16_f32 v66, v66, v67
	v_cvt_pk_bf16_f32 v67, v68, v69
	v_cvt_pk_bf16_f32 v68, v70, v71
	v_cvt_pk_bf16_f32 v69, v72, v73
	s_waitcnt lgkmcnt(2)
	s_nop 0
	v_mfma_f32_32x32x16_bf16 v[2:17], v[162:165], v[66:69], v[2:17]
	ds_read_b64 v[174:175], v221 offset:30496
	ds_read_b64 v[176:177], v221 offset:30512
	v_mfma_f32_32x32x16_bf16 v[18:33], v[166:169], v[66:69], v[18:33]
	ds_read_b64 v[180:181], v221 offset:26176
	ds_read_b64 v[182:183], v221 offset:26192
	v_exp_f32_e32 v74, v74
	v_exp_f32_e32 v75, v75
	v_exp_f32_e32 v76, v76
	v_exp_f32_e32 v77, v77
	v_add_f32_e32 v231, v231, v74
	v_add_f32_e32 v232, v232, v75
	v_exp_f32_e32 v78, v78
	v_exp_f32_e32 v79, v79
	v_add_f32_e32 v231, v231, v76
	v_add_f32_e32 v232, v232, v77
	v_exp_f32_e32 v80, v80
	v_exp_f32_e32 v81, v81
	v_add_f32_e32 v231, v231, v78
	v_add_f32_e32 v232, v232, v79
	v_add_f32_e32 v231, v231, v80
	v_add_f32_e32 v232, v232, v81
	v_cvt_pk_bf16_f32 v74, v74, v75
	v_cvt_pk_bf16_f32 v75, v76, v77
	v_cvt_pk_bf16_f32 v76, v78, v79
	v_cvt_pk_bf16_f32 v77, v80, v81
	s_waitcnt lgkmcnt(2)
	s_nop 0
	v_mfma_f32_32x32x16_bf16 v[2:17], v[170:173], v[74:77], v[2:17]
	ds_read_b64 v[184:185], v221 offset:30528
	ds_read_b64 v[186:187], v221 offset:30544
	v_mfma_f32_32x32x16_bf16 v[18:33], v[174:177], v[74:77], v[18:33]
	ds_read_b64 v[188:189], v221 offset:26208
	ds_read_b64 v[190:191], v221 offset:26224
	v_exp_f32_e32 v82, v82
	v_exp_f32_e32 v83, v83
	v_exp_f32_e32 v84, v84
	v_exp_f32_e32 v85, v85
	v_add_f32_e32 v231, v231, v82
	v_add_f32_e32 v232, v232, v83
	v_exp_f32_e32 v86, v86
	v_exp_f32_e32 v87, v87
	v_add_f32_e32 v231, v231, v84
	v_add_f32_e32 v232, v232, v85
	v_exp_f32_e32 v88, v88
	v_exp_f32_e32 v89, v89
	v_add_f32_e32 v231, v231, v86
	v_add_f32_e32 v232, v232, v87
	v_add_f32_e32 v231, v231, v88
	v_add_f32_e32 v232, v232, v89
	v_cvt_pk_bf16_f32 v82, v82, v83
	v_cvt_pk_bf16_f32 v83, v84, v85
	v_cvt_pk_bf16_f32 v84, v86, v87
	v_cvt_pk_bf16_f32 v85, v88, v89
	s_waitcnt lgkmcnt(2)
	s_nop 0
	v_mfma_f32_32x32x16_bf16 v[2:17], v[180:183], v[82:85], v[2:17]
	ds_read_b64 v[192:193], v221 offset:30560
	ds_read_b64 v[194:195], v221 offset:30576
	v_mfma_f32_32x32x16_bf16 v[18:33], v[184:187], v[82:85], v[18:33]
	v_exp_f32_e32 v90, v90
	v_exp_f32_e32 v91, v91
	v_exp_f32_e32 v92, v92
	v_exp_f32_e32 v93, v93
	v_add_f32_e32 v231, v231, v90
	v_add_f32_e32 v232, v232, v91
	v_exp_f32_e32 v94, v94
	v_exp_f32_e32 v95, v95
	v_add_f32_e32 v231, v231, v92
	v_add_f32_e32 v232, v232, v93
	v_exp_f32_e32 v96, v96
	v_exp_f32_e32 v97, v97
	v_add_f32_e32 v231, v231, v94
	v_add_f32_e32 v232, v232, v95
	v_add_f32_e32 v231, v231, v96
	v_add_f32_e32 v232, v232, v97
	v_cvt_pk_bf16_f32 v90, v90, v91
	v_cvt_pk_bf16_f32 v91, v92, v93
	v_cvt_pk_bf16_f32 v92, v94, v95
	v_cvt_pk_bf16_f32 v93, v96, v97
	s_waitcnt lgkmcnt(0)
	s_nop 0
	v_mfma_f32_32x32x16_bf16 v[2:17], v[188:191], v[90:93], v[2:17]
	v_mfma_f32_32x32x16_bf16 v[18:33], v[192:195], v[90:93], v[18:33]
	s_waitcnt lgkmcnt(0)
	s_barrier
	v_add_f32_e32 v231, v231, v232
	v_mov_b32_e32 v235, v231
	s_nop 1
	v_permlane32_swap_b32_e32 v231, v235
	v_add_f32_e32 v234, v231, v235
	v_div_scale_f32 v235, s[22:23], v234, v234, 1.0
	v_rcp_f32_e32 v179, v235
	v_div_scale_f32 v196, vcc, 1.0, v234, 1.0
	v_fma_f32 v197, -v235, v179, 1.0
	v_fmac_f32_e32 v179, v197, v179
	v_mul_f32_e32 v197, v196, v179
	v_fma_f32 v199, -v235, v197, v196
	v_fmac_f32_e32 v197, v199, v179
	v_fma_f32 v235, -v235, v197, v196
	v_div_fmas_f32 v235, v235, v179, v197
	v_div_fixup_f32 v234, v235, v234, 1.0
	s_nop 15
	v_mul_f32_e32 v2, v2, v234
	v_mul_f32_e32 v3, v3, v234
	v_mul_f32_e32 v4, v4, v234
	v_mul_f32_e32 v5, v5, v234
	v_mul_f32_e32 v6, v6, v234
	v_mul_f32_e32 v7, v7, v234
	v_mul_f32_e32 v8, v8, v234
	v_mul_f32_e32 v9, v9, v234
	v_mul_f32_e32 v10, v10, v234
	v_mul_f32_e32 v11, v11, v234
	v_mul_f32_e32 v12, v12, v234
	v_mul_f32_e32 v13, v13, v234
	v_mul_f32_e32 v14, v14, v234
	v_mul_f32_e32 v15, v15, v234
	v_mul_f32_e32 v16, v16, v234
	v_mul_f32_e32 v17, v17, v234
	v_mul_f32_e32 v18, v18, v234
	v_mul_f32_e32 v19, v19, v234
	v_mul_f32_e32 v20, v20, v234
	v_mul_f32_e32 v21, v21, v234
	v_mul_f32_e32 v22, v22, v234
	v_mul_f32_e32 v23, v23, v234
	v_mul_f32_e32 v24, v24, v234
	v_mul_f32_e32 v25, v25, v234
	v_mul_f32_e32 v26, v26, v234
	v_mul_f32_e32 v27, v27, v234
	v_mul_f32_e32 v28, v28, v234
	v_mul_f32_e32 v29, v29, v234
	v_mul_f32_e32 v30, v30, v234
	v_mul_f32_e32 v31, v31, v234
	v_mul_f32_e32 v32, v32, v234
	v_mul_f32_e32 v33, v33, v234
	s_cmpk_lt_i32 s2, 0x200
	s_cbranch_scc1 .Lmla_zw15
	s_waitcnt vmcnt(0)
	s_branch .Lmla_zw
.Lmla_zw15:
	s_waitcnt vmcnt(15)
.Lmla_zw:
	v_lshlrev_b32_e32 v179, 16, v200
	v_and_b32_e32 v196, 0xffff0000, v200
	v_lshlrev_b32_e32 v197, 16, v201
	v_and_b32_e32 v199, 0xffff0000, v201
	v_mul_f32_e32 v2, v2, v179
	v_mul_f32_e32 v3, v3, v196
	v_mul_f32_e32 v4, v4, v197
	v_mul_f32_e32 v5, v5, v199
	v_cvt_pk_bf16_f32 v200, v2, v3
	v_cvt_pk_bf16_f32 v201, v4, v5
	global_store_dwordx2 v236, v[200:201], s[24:25] offset:0
	v_lshlrev_b32_e32 v179, 16, v202
	v_and_b32_e32 v196, 0xffff0000, v202
	v_lshlrev_b32_e32 v197, 16, v203
	v_and_b32_e32 v199, 0xffff0000, v203
	v_mul_f32_e32 v6, v6, v179
	v_mul_f32_e32 v7, v7, v196
	v_mul_f32_e32 v8, v8, v197
	v_mul_f32_e32 v9, v9, v199
	v_cvt_pk_bf16_f32 v202, v6, v7
	v_cvt_pk_bf16_f32 v203, v8, v9
	global_store_dwordx2 v236, v[202:203], s[24:25] offset:16
	v_lshlrev_b32_e32 v179, 16, v204
	v_and_b32_e32 v196, 0xffff0000, v204
	v_lshlrev_b32_e32 v197, 16, v205
	v_and_b32_e32 v199, 0xffff0000, v205
	v_mul_f32_e32 v10, v10, v179
	v_mul_f32_e32 v11, v11, v196
	v_mul_f32_e32 v12, v12, v197
	v_mul_f32_e32 v13, v13, v199
	v_cvt_pk_bf16_f32 v204, v10, v11
	v_cvt_pk_bf16_f32 v205, v12, v13
	global_store_dwordx2 v236, v[204:205], s[24:25] offset:32
	v_lshlrev_b32_e32 v179, 16, v206
	v_and_b32_e32 v196, 0xffff0000, v206
	v_lshlrev_b32_e32 v197, 16, v207
	v_and_b32_e32 v199, 0xffff0000, v207
	v_mul_f32_e32 v14, v14, v179
	v_mul_f32_e32 v15, v15, v196
	v_mul_f32_e32 v16, v16, v197
	v_mul_f32_e32 v17, v17, v199
	v_cvt_pk_bf16_f32 v206, v14, v15
	v_cvt_pk_bf16_f32 v207, v16, v17
	global_store_dwordx2 v236, v[206:207], s[24:25] offset:48
	v_lshlrev_b32_e32 v179, 16, v208
	v_and_b32_e32 v196, 0xffff0000, v208
	v_lshlrev_b32_e32 v197, 16, v209
	v_and_b32_e32 v199, 0xffff0000, v209
	v_mul_f32_e32 v18, v18, v179
	v_mul_f32_e32 v19, v19, v196
	v_mul_f32_e32 v20, v20, v197
	v_mul_f32_e32 v21, v21, v199
	v_cvt_pk_bf16_f32 v208, v18, v19
	v_cvt_pk_bf16_f32 v209, v20, v21
	global_store_dwordx2 v236, v[208:209], s[24:25] offset:64
	v_lshlrev_b32_e32 v179, 16, v210
	v_and_b32_e32 v196, 0xffff0000, v210
	v_lshlrev_b32_e32 v197, 16, v211
	v_and_b32_e32 v199, 0xffff0000, v211
	v_mul_f32_e32 v22, v22, v179
	v_mul_f32_e32 v23, v23, v196
	v_mul_f32_e32 v24, v24, v197
	v_mul_f32_e32 v25, v25, v199
	v_cvt_pk_bf16_f32 v210, v22, v23
	v_cvt_pk_bf16_f32 v211, v24, v25
	global_store_dwordx2 v236, v[210:211], s[24:25] offset:80
	v_lshlrev_b32_e32 v179, 16, v212
	v_and_b32_e32 v196, 0xffff0000, v212
	v_lshlrev_b32_e32 v197, 16, v213
	v_and_b32_e32 v199, 0xffff0000, v213
	v_mul_f32_e32 v26, v26, v179
	v_mul_f32_e32 v27, v27, v196
	v_mul_f32_e32 v28, v28, v197
	v_mul_f32_e32 v29, v29, v199
	v_cvt_pk_bf16_f32 v212, v26, v27
	v_cvt_pk_bf16_f32 v213, v28, v29
	global_store_dwordx2 v236, v[212:213], s[24:25] offset:96
	v_lshlrev_b32_e32 v179, 16, v214
	v_and_b32_e32 v196, 0xffff0000, v214
	v_lshlrev_b32_e32 v197, 16, v215
	v_and_b32_e32 v199, 0xffff0000, v215
	v_mul_f32_e32 v30, v30, v179
	v_mul_f32_e32 v31, v31, v196
	v_mul_f32_e32 v32, v32, v197
	v_mul_f32_e32 v33, v33, v199
	v_cvt_pk_bf16_f32 v214, v30, v31
	v_cvt_pk_bf16_f32 v215, v32, v33
	global_store_dwordx2 v236, v[214:215], s[24:25] offset:112
	s_cmpk_lt_i32 s2, 0x200
	s_cbranch_scc0 .Lmla_exit
	v_mov_b32_e32 v2, 0
	v_mov_b32_e32 v3, 0
	v_mov_b32_e32 v4, 0
	v_mov_b32_e32 v5, 0
	v_mov_b32_e32 v6, 0
	v_mov_b32_e32 v7, 0
	v_mov_b32_e32 v8, 0
	v_mov_b32_e32 v9, 0
	v_mov_b32_e32 v10, 0
	v_mov_b32_e32 v11, 0
	v_mov_b32_e32 v12, 0
	v_mov_b32_e32 v13, 0
	v_mov_b32_e32 v14, 0
	v_mov_b32_e32 v15, 0
	v_mov_b32_e32 v16, 0
	v_mov_b32_e32 v17, 0
	v_mov_b32_e32 v18, 0
	v_mov_b32_e32 v19, 0
	v_mov_b32_e32 v20, 0
	v_mov_b32_e32 v21, 0
	v_mov_b32_e32 v22, 0
	v_mov_b32_e32 v23, 0
	v_mov_b32_e32 v24, 0
	v_mov_b32_e32 v25, 0
	v_mov_b32_e32 v26, 0
	v_mov_b32_e32 v27, 0
	v_mov_b32_e32 v28, 0
	v_mov_b32_e32 v29, 0
	v_mov_b32_e32 v30, 0
	v_mov_b32_e32 v31, 0
	v_mov_b32_e32 v32, 0
	v_mov_b32_e32 v33, 0
	v_mov_b32_e32 v122, 0
	v_mov_b32_e32 v123, 0
	v_mov_b32_e32 v124, 0
	v_mov_b32_e32 v125, 0
	v_mov_b32_e32 v126, 0
	v_mov_b32_e32 v127, 0
	v_mov_b32_e32 v128, 0
	v_mov_b32_e32 v129, 0
	v_mov_b32_e32 v130, 0
	v_mov_b32_e32 v131, 0
	v_mov_b32_e32 v132, 0
	v_mov_b32_e32 v133, 0
	v_mov_b32_e32 v134, 0
	v_mov_b32_e32 v135, 0
	v_mov_b32_e32 v136, 0
	v_mov_b32_e32 v137, 0
	v_mov_b32_e32 v230, 0
	v_mov_b32_e32 v231, 0
	v_mov_b32_e32 v232, 0
	s_waitcnt vmcnt(13)
	ds_write_b128 v222, v[34:37]
	ds_write_b128 v223, v[38:41]
	ds_write_b128 v224, v[42:45]
	ds_write_b64 v225, v[46:47]
	ds_write_b64 v225, v[48:49] offset:8
	s_waitcnt vmcnt(9)
	ds_write_b128 v222, v[50:53] offset:26624
	ds_write_b128 v223, v[54:57] offset:26624
	ds_write_b128 v224, v[58:61] offset:26624
	ds_write_b64 v225, v[62:63] offset:8704
	ds_write_b64 v225, v[64:65] offset:8712
	s_waitcnt lgkmcnt(0)
	s_barrier
	s_branch .Lmla_body
.Lmla_exit:
.LBB0_1920:
	s_cmp_gt_i32 s83, 5
	s_cselect_b64 s[0:1], -1, 0
	s_and_b64 s[2:3], s[46:47], s[0:1]
	s_andn2_b64 vcc, exec, s[2:3]
	s_cbranch_vccnz .LBB0_1974
	s_waitcnt vmcnt(0)
	s_waitcnt vmcnt(0) lgkmcnt(0)
	s_barrier
	s_and_saveexec_b64 s[4:5], s[52:53]
	s_cbranch_execz .LBB0_1973
	s_add_i32 s2, 0, 0x20160
	v_mov_b32_e32 v1, s2
	s_waitcnt vmcnt(0) expcnt(0) lgkmcnt(0)
	ds_read_b32 v3, v1
	s_add_i32 s2, 0, 0x20164
	v_mov_b32_e32 v1, s2
	ds_read_b32 v1, v1
	s_waitcnt lgkmcnt(1)
	v_cmp_ne_u32_e32 vcc, 0, v3
	s_cbranch_vccnz .LBB0_1937
	v_readlane_b32 s6, v251, 0
	v_readlane_b32 s7, v251, 1
	s_load_dwordx2 s[2:3], s[6:7], 0x4
	s_add_u32 s6, s80, 0x1200
	s_addc_u32 s7, s81, 0
	s_add_u32 s8, s80, 0x1400
	s_addc_u32 s9, s81, 0
	s_add_u32 s10, s80, 0x1500
	s_addc_u32 s11, s81, 0
	s_add_u32 s12, s80, 0x1600
	s_addc_u32 s13, s81, 0
	s_add_u32 s14, s80, 0x1700
	s_addc_u32 s15, s81, 0
	s_add_u32 s16, s80, 0x1800
	s_addc_u32 s17, s81, 0
	s_add_u32 s18, s80, 0x1900
	s_addc_u32 s19, s81, 0
	s_add_u32 s20, s80, 0x1a00
	s_addc_u32 s21, s81, 0
	s_add_u32 s22, s80, 0x1b00
	s_addc_u32 s23, s81, 0
	s_add_u32 s24, s80, 0x1c00
	s_addc_u32 s25, s81, 0
	s_add_u32 s26, s80, 0x1d00
	s_addc_u32 s27, s81, 0
	s_add_u32 s28, s80, 0x1e00
	s_addc_u32 s29, s81, 0
	s_add_u32 s30, s80, 0x1f00
	s_addc_u32 s31, s81, 0
	s_add_u32 s34, s80, 0x2000
	s_addc_u32 s35, s81, 0
	s_add_u32 s36, s80, 0x2100
	s_addc_u32 s37, s81, 0
	s_add_u32 s38, s80, 0x2200
	s_addc_u32 s39, s81, 0
	s_waitcnt lgkmcnt(0)
	s_mul_i32 s2, s2, s88
	s_add_u32 s40, s80, 0x2300
	s_mul_i32 s2, s2, s3
	s_addc_u32 s41, s81, 0
	s_mov_b32 s3, 1
	v_mov_b32_e32 v17, 0
	s_branch .LBB0_1925
